# MoBA chunk units: rescale threshold +inf under the runtime bound on the MoBA q/k-norm gains (rescale path ran on almost every tile before)
# baseline (speedup 1.0000x reference)
; #define LAS __attribute__((address_space(3)))
; __device__ __forceinline__ int opaque_tid() { int t = threadIdx.x; asm volatile("" : "+v"(t)); return t; }
; #define WSPTR() ({ unsigned char* w_ = ARGS().ws; asm volatile("" : "+s"(w_)); w_; })
; __global__ void __launch_bounds__(NWAVES * 64, 2) mega_fwd(Args args_) {
;     ...
;             { unsigned char* ws = WSPTR(); const int l = step / 3; const int tid = opaque_tid();
;               volatile LAS unsigned* MISC = (volatile LAS unsigned*)(ldsl + MISC_OFF);
;               volatile LAS int* T = (volatile LAS int*)(ldsl + MISC_OFF + 1024);
;               unsigned* qctr = (unsigned*)(ws + WS_CTL) + 64 * (1 + l);
;               const attn_body::bf16* QKV = (const attn_body::bf16*)(ws + WS_R1); attn_body::bf16* OBa = (attn_body::bf16*)(ws + WS_OB);
;               const int TC = T[772];
;               for (;;) {
;                   if (tid == 0) MISC[0] = atomicAdd(qctr, 1u);
;                   __syncthreads(); const int u = __builtin_amdgcn_readfirstlane((int)MISC[0]); __syncthreads();
.LBB0_1073:
	s_or_b64 exec, exec, s[0:1]
	s_mov_b64 s[0:1], s[84:85]
	s_waitcnt lgkmcnt(0)
	s_barrier
	s_load_dwordx2 s[16:17], s[0:1], 0xe0
	v_readlane_b32 s0, v254, 45
	s_lshl_b32 s0, s0, 2
	s_waitcnt lgkmcnt(0)
	s_add_u32 s18, s16, s0
	s_addc_u32 s19, s17, 0
	s_add_u32 s14, s16, 0x5c00000
	s_addc_u32 s15, s17, 0
	s_add_u32 s37, s16, 0x5c00600
	s_addc_u32 s38, s17, 0
	s_add_u32 s39, s16, 0x5c00800
	s_addc_u32 s42, s17, 0
	s_add_u32 s43, s16, 0x5c00900
	v_readlane_b32 s1, v254, 33
	s_addc_u32 s44, s17, 0
	s_add_u32 s45, s16, 0xb400200
	v_mov_b32_e32 v1, s1
	v_readlane_b32 s0, v254, 15
	s_addc_u32 s46, s17, 0
	v_readlane_b32 s1, v254, 16
	s_and_b64 s[0:1], s[0:1], exec
	s_cselect_b32 s47, 4, 0
	s_add_u32 s48, s16, 0xe400000
	s_addc_u32 s49, s17, 0
	s_add_u32 s50, s16, 0x800000
	s_addc_u32 s51, s17, 0
	s_add_u32 s52, s16, 0x5c00200
	s_addc_u32 s53, s17, 0
	s_add_u32 s54, s16, 0x5c00400
	s_addc_u32 s55, s17, 0
	s_add_u32 s56, s16, 0xfc00000
	s_addc_u32 s57, s17, 0
	s_add_u32 s58, s16, 0xfe00000
	s_addc_u32 s59, s17, 0
	v_mov_b32_e32 v0, v230
	s_add_u32 s60, s16, 0x5c00a00
	ds_read_b32 v1, v1
	s_addc_u32 s61, s17, 0
	s_add_u32 s62, s16, 0x5c00e00
	s_addc_u32 s63, s17, 0
	s_add_u32 s64, s16, 0x5c01200
	s_addc_u32 s65, s17, 0
	s_waitcnt lgkmcnt(0)
	v_readfirstlane_b32 s36, v1
	s_add_u32 s66, s16, 0xb400400
	v_cmp_eq_u32_e64 s[6:7], 0, v0
	v_add_u32_e32 v245, 0x400, v1
	v_add_u32_e32 v246, 0x500, v1
	s_addc_u32 s67, s17, 0
	s_sub_i32 s68, 0, s36
	v_mbcnt_lo_u32_b32 v0, -1, 0
	v_mbcnt_hi_u32_b32 v0, -1, v0
	v_lshlrev_b32_e32 v0, 2, v0
	v_lshl_add_u32 v0, s47, 6, v0
	s_load_dwordx2 s[0:1], s[84:85], 0x60
	s_waitcnt lgkmcnt(0)
	global_load_dword v1, v0, s[0:1]
	s_load_dwordx2 s[0:1], s[84:85], 0x68
	s_waitcnt lgkmcnt(0)
	global_load_dword v0, v0, s[0:1]
	s_waitcnt vmcnt(0)
	v_max_f32_e64 v0, |v0|, |v1|
	v_cmp_gt_f32_e32 vcc, 0x3fd9999a, v0
	s_nop 1
	s_cmp_eq_u64 vcc, exec
	s_cselect_b32 s32, 1, 0
	v_mbcnt_lo_u32_b32 v0, -1, 0
	v_mbcnt_hi_u32_b32 v0, -1, v0
	v_lshlrev_b32_e32 v0, 2, v0
	v_lshl_add_u32 v0, s47, 6, v0
	s_load_dwordx2 s[0:1], s[84:85], 0x38
	s_waitcnt lgkmcnt(0)
	global_load_dword v1, v0, s[0:1]
	s_load_dwordx2 s[0:1], s[84:85], 0x40
	s_waitcnt lgkmcnt(0)
	global_load_dword v0, v0, s[0:1]
	s_waitcnt vmcnt(0)
	v_max_f32_e64 v0, |v0|, |v1|
	v_cmp_gt_f32_e32 vcc, 0x3fd9999a, v0
	s_nop 1
	s_cmp_eq_u64 vcc, exec
	s_cselect_b32 s0, 4, 0
	s_or_b32 s32, s32, s0
	v_mov_b32_e32 v1, 0x21800
	v_lshl_add_u32 v0, v230, 2, v1
	ds_write_b32 v0, v241
	s_waitcnt lgkmcnt(0)
	s_mov_b64 s[0:1], exec
	s_and_b64 exec, exec, s[6:7]
	s_cbranch_execz .Ltk_setup
	global_atomic_add v241, v113, v235, s[18:19] offset:256 sc0

.LBB0_1106:
	s_and_b64 vcc, exec, s[0:1]
	s_cbranch_vccz .LBB0_1203
	s_mov_b32 s27, 0
	s_bitcmp1_b32 s32, 2
	s_cselect_b32 s27, 0x7f800000, s27
	s_add_i32 s2, s69, 0xfffffc00
	s_movk_i32 s0, 0xff
	s_mov_b32 s3, 0

; #define WAIT_BAR(N) asm volatile("s_waitcnt vmcnt(" #N ") lgkmcnt(0)\n\ts_barrier":::"memory")
;   #define DMA_K(t,slot) glds16(ksrc+(long)(t)*KVBLK*DM,(unsigned)__builtin_amdgcn_readfirstlane(kdst+(slot)))
;   #define DMA_V(t,slot) glds16(vsrc+(long)(t)*KVBLK*DM,(unsigned)__builtin_amdgcn_readfirstlane(vdst+(slot)))
;   #define CMASK(P0,P1,t) do{int jb_=(t)-(NT-4); if(MODE==3){ if(!list&&jb_>=0)cmask(P0,P1,jb_,qrel,hi); } else if(MODE==2){swamask(P0,P1,jb_,qrel,hi);} else if(jb_>=0){cmask(P0,P1,jb_,qrel,hi);} else if(MODE==1){mobamask(P0,P1,sel,(t)>>2);} }while(0)
;   #define START(P0,P1) do{ const float rm=rowmax(P0,P1); resc=false; \
;     { const float dl=rm; mhat=fadd_s(mhat,dl); \
;       _Pragma("unroll") for(int r=0;r<16;++r){P0[r]=fsub_s(P0[r],dl);P1[r]=fsub_s(P1[r],dl);} \
;       _Pragma("unroll") for(int r=0;r<16;++r)negm[r]=-mhat; asm volatile("":"+v"(negm)); } \
;     _Pragma("unroll") for(int r=0;r<16;++r)P0[r]=__builtin_amdgcn_exp2f(P0[r]); }while(0)
;   #define ROT() do{sl_prev=sl_cur;sl_cur=sl_next;sl_next=(sl_next==(NSLOT-1)*SLOTB)?0:sl_next+SLOTB;}while(0)
;   #define CMASK(P0,P1,t) do{ if(MODE==1){mobamask(P0,P1,sel,(t)>>2);} }while(0)
;   #define CMASK(P0,P1,t) do{int jb_=(t)-(NT-4); if(MODE==3){ if(!list&&jb_>=0)cmask(P0,P1,jb_,qrel,hi); } else if(MODE==2){swamask(P0,P1,jb_,qrel,hi);} else if(jb_>=0){cmask(P0,P1,jb_,qrel,hi);} else if(MODE==1){mobamask(P0,P1,sel,(t)>>2);} }while(0)
;     ...
;   f32x16 pA0,pA1,pB0,pB1;
;   int sl_prev=0,sl_cur=0,sl_next=SLOTB;
;     ...
;   DMA_K(2,2*SLOTB);
;   WAIT_BAR(3);
;   qkt(pA0,pA1,Kbase,qr,negm,r32,hi);asm volatile("s_nop 15\n\ts_nop 7":"+v"(pA0),"+v"(pA1));CMASK(pA0,pA1,0);
;   START(pA0,pA1);
;   _Pragma("unroll") for(int r=0;r<16;++r)pA1[r]=__builtin_amdgcn_exp2f(pA1[r]);
;   WAIT_BAR(0);
;   DMA_K(3,0);DMA_V(1,SLOTB);
;   ROT();
;   kload8(kf,kp0+sl_cur);
;   WAIT_BAR(2);
.LBB0_1119:
	v_lshlrev_b32_e32 v33, 1, v32
	v_lshlrev_b32_e32 v32, 4, v32
	v_and_b32_e32 v195, 32, v33
	v_and_b32_e32 v32, 0xc0, v32
	v_lshl_or_b32 v194, v192, 8, v32
	v_add_u32_e32 v32, 0, v195
	v_add3_u32 v198, v32, v183, v194
	v_max3_f32 v32, v16, v17, v0
	v_max3_f32 v33, v18, v19, v1
	s_and_b32 s1, s2, 0x3fffffc0
	v_max3_f32 v32, v32, v2, v3
	v_max3_f32 v33, v33, v22, v23
	s_lshl_b32 s1, s1, 2
	v_max3_f32 v32, v32, v20, v21
	v_max3_f32 v33, v33, v6, v7
	s_add_i32 s5, s1, 0
	v_max3_f32 v32, v32, v4, v5
	v_max3_f32 v33, v33, v26, v27
	s_mov_b64 s[2:3], 0x108000
	v_max3_f32 v32, v32, v24, v25
	v_max3_f32 v33, v33, v10, v11
	s_cmp_lg_u32 0, -1
	v_max3_f32 v32, v32, v8, v9
	v_max3_f32 v33, v33, v30, v31
	s_mov_b32 s24, 1
	v_max3_f32 v32, v32, v28, v29
	v_max3_f32 v33, v33, v14, v15
	s_mov_b32 s1, 0
	v_max3_f32 v32, v32, v12, v13
	v_cmp_gt_u32_e64 s[8:9], 32, v189
	v_max_f32_e32 v32, v32, v33
	v_lshl_add_u32 v196, v190, 2, s5
	v_mov_b32_e32 v33, v32
	s_nop 1
	v_permlane32_swap_b32_e32 v32, v33
	v_max_f32_e32 v32, v32, v33
	s_nop 0
	v_add_f32_e32 v193, v113, v32
	v_sub_f32_e32 v33, v0, v32
	v_sub_f32_e32 v16, v16, v32
	v_sub_f32_e32 v17, v17, v32
	v_sub_f32_e32 v34, v1, v32
	v_sub_f32_e32 v18, v18, v32
	s_nop 0
	v_xor_b32_e32 v0, 0x80000000, v193
	v_sub_f32_e32 v35, v2, v32
	v_sub_f32_e32 v19, v19, v32
	v_sub_f32_e32 v36, v3, v32
	v_sub_f32_e32 v20, v20, v32
	v_sub_f32_e32 v37, v4, v32
	v_sub_f32_e32 v21, v21, v32
	v_sub_f32_e32 v38, v5, v32
	v_sub_f32_e32 v22, v22, v32
	v_sub_f32_e32 v39, v6, v32
	v_sub_f32_e32 v23, v23, v32
	v_sub_f32_e32 v40, v7, v32
	v_sub_f32_e32 v24, v24, v32
	v_sub_f32_e32 v41, v8, v32
	v_sub_f32_e32 v25, v25, v32
	v_sub_f32_e32 v42, v9, v32
	v_sub_f32_e32 v26, v26, v32
	v_sub_f32_e32 v43, v10, v32
	v_sub_f32_e32 v27, v27, v32
	v_sub_f32_e32 v44, v11, v32
	v_sub_f32_e32 v28, v28, v32
	v_sub_f32_e32 v45, v12, v32
	v_sub_f32_e32 v29, v29, v32
	v_sub_f32_e32 v46, v13, v32
	v_sub_f32_e32 v30, v30, v32
	v_sub_f32_e32 v47, v14, v32
	v_sub_f32_e32 v31, v31, v32
	v_sub_f32_e32 v32, v15, v32
	v_mov_b32_e32 v1, v0
	v_mov_b32_e32 v2, v0
	v_mov_b32_e32 v3, v0
	v_mov_b32_e32 v4, v0
	v_mov_b32_e32 v5, v0
	v_mov_b32_e32 v6, v0
	v_mov_b32_e32 v7, v0
	v_mov_b32_e32 v8, v0
	v_mov_b32_e32 v9, v0
	v_mov_b32_e32 v10, v0
	v_mov_b32_e32 v11, v0
	v_mov_b32_e32 v12, v0
	v_mov_b32_e32 v13, v0
	v_mov_b32_e32 v14, v0
	v_mov_b32_e32 v15, v0
	s_waitcnt vmcnt(0) lgkmcnt(0)
	s_barrier
	v_exp_f32_e32 v64, v16
	v_exp_f32_e32 v65, v17
	v_lshl_add_u64 v[16:17], v[186:187], 0, s[2:3]
	s_mov_b32 s2, m0
	s_mov_b32 m0, s0
	s_nop 0
	global_load_lds_dwordx4 v[16:17], off
	s_mov_b32 m0, s2
	s_cselect_b32 s0, 0, 0
	s_add_i32 s0, s0, s13
	v_lshl_add_u64 v[16:17], v[184:185], 0, s[78:79]
	s_add_i32 s0, s0, 0x8000
	s_mov_b32 s2, m0
	s_mov_b32 m0, s0
	s_nop 0
	global_load_lds_dwordx4 v[16:17], off
	s_mov_b32 m0, s2
	ds_read_b128 v[174:177], v199 offset:8192
	ds_read_b128 v[170:173], v199 offset:8704
	ds_read_b128 v[166:169], v199 offset:10240
	ds_read_b128 v[162:165], v199 offset:10752
	ds_read_b128 v[158:161], v199 offset:12288
	ds_read_b128 v[154:157], v199 offset:12800
	ds_read_b128 v[150:153], v199 offset:14336
	ds_read_b128 v[146:149], v199 offset:14848
	v_exp_f32_e32 v66, v18
	v_exp_f32_e32 v67, v19
	v_exp_f32_e32 v68, v20
	v_exp_f32_e32 v69, v21
	v_exp_f32_e32 v70, v22
	v_exp_f32_e32 v71, v23
	v_exp_f32_e32 v72, v24
	v_exp_f32_e32 v73, v25
	v_exp_f32_e32 v74, v26
	v_exp_f32_e32 v75, v27
	v_exp_f32_e32 v76, v28
	v_exp_f32_e32 v77, v29
	v_exp_f32_e32 v78, v30
	v_exp_f32_e32 v79, v31
	v_exp_f32_e32 v48, v33
	v_exp_f32_e32 v49, v34
	v_exp_f32_e32 v50, v35
	v_exp_f32_e32 v51, v36
	v_exp_f32_e32 v52, v37
	v_exp_f32_e32 v53, v38
	v_exp_f32_e32 v54, v39
	v_exp_f32_e32 v55, v40
	v_exp_f32_e32 v56, v41
	v_exp_f32_e32 v57, v42
	v_exp_f32_e32 v58, v43
	v_exp_f32_e32 v59, v44
	v_exp_f32_e32 v60, v45
	v_exp_f32_e32 v61, v46
	v_exp_f32_e32 v62, v47
	v_exp_f32_e32 v63, v32
	s_waitcnt vmcnt(2) lgkmcnt(0)
	s_barrier
	s_cmp_lt_i32 s12, 7
	s_cselect_b64 s[34:35], -1, 0
	s_and_b64 vcc, exec, s[34:35]
	s_cbranch_vccnz .LBB0_1174
	ds_read_b64_tr_b16 v[20:21], v198 offset:24576
	ds_read_b64_tr_b16 v[22:23], v198 offset:25088
	s_waitcnt lgkmcnt(9)
	v_mfma_f32_32x32x16_bf16 v[96:111], v[174:177], v[126:129], v[0:15]
	v_add_f32_e32 v16, v64, v65
	v_add_f32_e32 v16, v66, v16
	v_add_f32_e32 v16, v67, v16
	v_add_f32_e32 v16, v68, v16
	v_add_f32_e32 v24, v69, v16
	v_cvt_pk_bf16_f32 v130, v64, v65
	v_cvt_pk_bf16_f32 v131, v66, v67
	ds_read_b64_tr_b16 v[16:17], v198 offset:28672
	ds_read_b64_tr_b16 v[18:19], v198 offset:29184
	v_mov_b64_e32 v[94:95], v[14:15]
	v_mov_b64_e32 v[92:93], v[12:13]
	v_mov_b64_e32 v[90:91], v[10:11]
	v_mov_b64_e32 v[88:89], v[8:9]
	v_mov_b64_e32 v[86:87], v[6:7]
	v_mov_b64_e32 v[84:85], v[4:5]
	v_mov_b64_e32 v[82:83], v[2:3]
	v_mov_b64_e32 v[80:81], v[0:1]
	v_add_f32_e32 v24, v70, v24
	v_add_f32_e32 v24, v71, v24
	s_waitcnt lgkmcnt(10)
	v_mfma_f32_32x32x16_bf16 v[80:95], v[170:173], v[126:129], v[80:95]
	v_add_f32_e32 v24, v72, v24
	v_add_f32_e32 v24, v73, v24
	v_cvt_pk_bf16_f32 v132, v68, v69
	v_cvt_pk_bf16_f32 v133, v70, v71
	ds_read_b64_tr_b16 v[64:65], v198 offset:25600
	ds_read_b64_tr_b16 v[66:67], v198 offset:26112
	s_waitcnt lgkmcnt(11)
	v_mfma_f32_32x32x16_bf16 v[96:111], v[166:169], v[122:125], v[96:111]
	v_add_f32_e32 v24, v74, v24
	v_add_f32_e32 v24, v75, v24
	v_add_f32_e32 v24, v76, v24
	v_add_f32_e32 v24, v77, v24
	v_cvt_pk_bf16_f32 v134, v72, v73
	v_cvt_pk_bf16_f32 v135, v74, v75
	ds_read_b64_tr_b16 v[68:69], v198 offset:29696
	ds_read_b64_tr_b16 v[70:71], v198 offset:30208
	s_waitcnt lgkmcnt(12)
	v_mfma_f32_32x32x16_bf16 v[80:95], v[162:165], v[122:125], v[80:95]
	v_add_f32_e32 v24, v78, v24
	v_add_f32_e32 v24, v79, v24
	v_add_f32_e32 v24, v48, v24
	v_add_f32_e32 v24, v49, v24
	v_cvt_pk_bf16_f32 v136, v76, v77
	v_cvt_pk_bf16_f32 v137, v78, v79
	ds_read_b64_tr_b16 v[72:73], v198 offset:26624
	ds_read_b64_tr_b16 v[74:75], v198 offset:27136
	s_waitcnt lgkmcnt(13)
	v_mfma_f32_32x32x16_bf16 v[96:111], v[158:161], v[118:121], v[96:111]
	v_add_f32_e32 v24, v50, v24
	v_add_f32_e32 v24, v51, v24
	v_add_f32_e32 v24, v52, v24
	v_add_f32_e32 v24, v53, v24
	v_cvt_pk_bf16_f32 v138, v48, v49
	v_cvt_pk_bf16_f32 v139, v50, v51
	ds_read_b64_tr_b16 v[48:49], v198 offset:30720
	ds_read_b64_tr_b16 v[50:51], v198 offset:31232
	s_waitcnt lgkmcnt(14)
	v_mfma_f32_32x32x16_bf16 v[80:95], v[154:157], v[118:121], v[80:95]
	v_add_f32_e32 v24, v54, v24
	v_add_f32_e32 v24, v55, v24
	v_add_f32_e32 v24, v56, v24
	v_add_f32_e32 v24, v57, v24
	v_cvt_pk_bf16_f32 v140, v52, v53
	v_cvt_pk_bf16_f32 v141, v54, v55
	ds_read_b64_tr_b16 v[52:53], v198 offset:27648
	ds_read_b64_tr_b16 v[54:55], v198 offset:28160
	s_waitcnt lgkmcnt(14)
	v_mfma_f32_32x32x16_bf16 v[96:111], v[150:153], v[114:117], v[96:111]
	v_add_f32_e32 v24, v58, v24
	v_add_f32_e32 v24, v59, v24
	v_add_f32_e32 v24, v60, v24
	v_add_f32_e32 v24, v61, v24
	v_cvt_pk_bf16_f32 v142, v56, v57
	v_cvt_pk_bf16_f32 v143, v58, v59
	ds_read_b64_tr_b16 v[56:57], v198 offset:31744
	ds_read_b64_tr_b16 v[58:59], v198 offset:32256
	v_mfma_f32_32x32x16_bf16 v[80:95], v[146:149], v[114:117], v[80:95]
	v_add_f32_e32 v24, v62, v24
	v_add_f32_e32 v24, v63, v24
	v_add_f32_e32 v26, 0, v24
	v_cvt_pk_bf16_f32 v144, v60, v61
	v_cvt_pk_bf16_f32 v145, v62, v63
	s_mov_b64 s[0:1], 0x160000
	s_cmp_lg_u32 0, -1
	v_lshl_add_u64 v[24:25], v[186:187], 0, s[0:1]
	s_cselect_b32 s0, 0, 0
	s_add_i32 s0, s0, s13
	s_add_i32 s1, s0, 0x2000
	s_mov_b32 s2, m0
	s_mov_b32 m0, s1
	s_nop 0
	global_load_lds_dwordx4 v[24:25], off
	s_mov_b32 m0, s2
	v_lshl_add_u64 v[24:25], v[184:185], 0, s[94:95]
	s_add_i32 s0, s0, 0xa000
	s_mov_b32 s1, m0
	s_mov_b32 m0, s0
	s_nop 0
	global_load_lds_dwordx4 v[24:25], off
	s_mov_b32 m0, s1
	v_max_f32_e32 v24, v97, v97
	v_max_f32_e32 v25, v96, v96
	v_max_f32_e32 v24, v25, v24
	v_max3_f32 v25, v98, v99, v81
	v_max3_f32 v24, v24, v80, v82
	v_max3_f32 v24, v24, v83, v100
	v_max3_f32 v25, v25, v102, v103
	v_max3_f32 v24, v24, v101, v84
	v_max3_f32 v25, v25, v86, v87
	v_max3_f32 v24, v24, v85, v104
	v_max3_f32 v25, v25, v106, v107
	v_max3_f32 v24, v24, v105, v88
	v_max3_f32 v25, v25, v90, v91
	v_max3_f32 v24, v24, v89, v108
	v_max3_f32 v25, v25, v110, v111
	v_max3_f32 v24, v24, v109, v92
	v_max3_f32 v25, v25, v94, v95
	v_max3_f32 v24, v24, v93, v25
	v_mov_b32_e32 v25, v24
	s_nop 1
	v_permlane32_swap_b32_e32 v24, v25
	v_max_f32_e32 v25, v25, v25
	v_max_f32_e32 v24, v24, v24
	v_max_f32_e32 v24, v24, v25
	v_cmp_lt_f32_e32 vcc, s27, v24
	s_cmp_lg_u64 vcc, 0
	v_add_f32_e32 v201, 0, v26
	s_cselect_b64 s[0:1], -1, 0
	s_cbranch_vccnz .LBB0_1290

.LBB0_1123:
	ds_read_b64_tr_b16 v[150:151], v198 offset:32768
	ds_read_b64_tr_b16 v[152:153], v198 offset:33280
	s_waitcnt lgkmcnt(9)
	v_mfma_f32_32x32x16_bf16 v[64:79], v[60:63], v[126:129], v[0:15]
	v_add_f32_e32 v48, v96, v97
	v_add_f32_e32 v48, v98, v48
	v_add_f32_e32 v48, v99, v48
	v_add_f32_e32 v48, v100, v48
	v_add_f32_e32 v48, v101, v48
	v_cvt_pk_bf16_f32 v130, v96, v97
	v_cvt_pk_bf16_f32 v131, v98, v99
	ds_read_b64_tr_b16 v[146:147], v198 offset:36864
	ds_read_b64_tr_b16 v[148:149], v198 offset:37376
	v_add_f32_e32 v48, v102, v48
	v_add_f32_e32 v48, v103, v48
	v_add_f32_e32 v48, v104, v48
	v_add_f32_e32 v134, v105, v48
	s_waitcnt lgkmcnt(10)
	v_mfma_f32_32x32x16_bf16 v[48:63], v[174:177], v[126:129], v[0:15]
	v_cvt_pk_bf16_f32 v132, v100, v101
	v_cvt_pk_bf16_f32 v133, v102, v103
	ds_read_b64_tr_b16 v[96:97], v198 offset:33792
	ds_read_b64_tr_b16 v[98:99], v198 offset:34304
	s_waitcnt lgkmcnt(11)
	v_mfma_f32_32x32x16_bf16 v[64:79], v[178:181], v[122:125], v[64:79]
	v_add_f32_e32 v100, v106, v134
	v_add_f32_e32 v100, v107, v100
	v_add_f32_e32 v100, v108, v100
	v_add_f32_e32 v138, v109, v100
	v_cvt_pk_bf16_f32 v134, v104, v105
	v_cvt_pk_bf16_f32 v135, v106, v107
	ds_read_b64_tr_b16 v[100:101], v198 offset:37888
	ds_read_b64_tr_b16 v[102:103], v198 offset:38400
	s_waitcnt lgkmcnt(12)
	v_mfma_f32_32x32x16_bf16 v[48:63], v[170:173], v[122:125], v[48:63]
	v_add_f32_e32 v104, v110, v138
	v_add_f32_e32 v104, v111, v104
	v_add_f32_e32 v104, v80, v104
	v_add_f32_e32 v138, v81, v104
	v_cvt_pk_bf16_f32 v136, v108, v109
	v_cvt_pk_bf16_f32 v137, v110, v111
	ds_read_b64_tr_b16 v[104:105], v198 offset:34816
	ds_read_b64_tr_b16 v[106:107], v198 offset:35328
	s_waitcnt lgkmcnt(13)
	v_mfma_f32_32x32x16_bf16 v[64:79], v[166:169], v[118:121], v[64:79]
	v_add_f32_e32 v108, v82, v138
	v_add_f32_e32 v108, v83, v108
	v_add_f32_e32 v108, v84, v108
	v_add_f32_e32 v108, v85, v108
	v_cvt_pk_bf16_f32 v138, v80, v81
	v_cvt_pk_bf16_f32 v139, v82, v83
	ds_read_b64_tr_b16 v[80:81], v198 offset:38912
	ds_read_b64_tr_b16 v[82:83], v198 offset:39424
	s_waitcnt lgkmcnt(14)
	v_mfma_f32_32x32x16_bf16 v[48:63], v[162:165], v[118:121], v[48:63]
	v_add_f32_e32 v108, v86, v108
	v_add_f32_e32 v108, v87, v108
	v_add_f32_e32 v108, v88, v108
	v_add_f32_e32 v108, v89, v108
	v_cvt_pk_bf16_f32 v140, v84, v85
	v_cvt_pk_bf16_f32 v141, v86, v87
	ds_read_b64_tr_b16 v[84:85], v198 offset:35840
	ds_read_b64_tr_b16 v[86:87], v198 offset:36352
	s_waitcnt lgkmcnt(14)
	v_mfma_f32_32x32x16_bf16 v[64:79], v[158:161], v[114:117], v[64:79]
	v_add_f32_e32 v108, v90, v108
	v_add_f32_e32 v108, v91, v108
	v_add_f32_e32 v108, v92, v108
	v_add_f32_e32 v108, v93, v108
	v_cvt_pk_bf16_f32 v142, v88, v89
	v_cvt_pk_bf16_f32 v143, v90, v91
	ds_read_b64_tr_b16 v[88:89], v198 offset:39936
	ds_read_b64_tr_b16 v[90:91], v198 offset:40448
	v_mfma_f32_32x32x16_bf16 v[48:63], v[154:157], v[114:117], v[48:63]
	v_add_f32_e32 v108, v94, v108
	v_add_f32_e32 v108, v95, v108
	v_add_f32_e32 v108, 0, v108
	v_cvt_pk_bf16_f32 v144, v92, v93
	v_cvt_pk_bf16_f32 v145, v94, v95
	s_mov_b64 s[0:1], 0x1b8000
	s_cmp_lg_u32 0, -1
	v_lshl_add_u64 v[92:93], v[186:187], 0, s[0:1]
	s_cselect_b32 s0, 0, 0
	s_add_i32 s0, s0, s13
	s_addk_i32 s0, 0x4000
	s_mov_b32 s1, m0
	s_mov_b32 m0, s0
	s_nop 0
	global_load_lds_dwordx4 v[92:93], off
	s_mov_b32 m0, s1
	s_mov_b64 s[0:1], 0x108000
	v_lshl_add_u64 v[92:93], v[184:185], 0, s[0:1]
	s_mov_b32 s0, m0
	s_mov_b32 m0, s11
	s_nop 0
	global_load_lds_dwordx4 v[92:93], off
	s_mov_b32 m0, s0
	v_max_f32_e32 v92, v65, v65
	v_max_f32_e32 v93, v64, v64
	v_max_f32_e32 v92, v93, v92
	v_max3_f32 v93, v66, v67, v49
	v_max3_f32 v92, v92, v48, v50
	v_max3_f32 v92, v92, v51, v68
	v_max3_f32 v93, v93, v70, v71
	v_max3_f32 v92, v92, v69, v52
	v_max3_f32 v93, v93, v54, v55
	v_max3_f32 v92, v92, v53, v72
	v_max3_f32 v93, v93, v74, v75
	v_max3_f32 v92, v92, v73, v56
	v_max3_f32 v93, v93, v58, v59
	v_max3_f32 v92, v92, v57, v76
	v_max3_f32 v93, v93, v78, v79
	v_max3_f32 v92, v92, v77, v60
	v_max3_f32 v93, v93, v62, v63
	v_max3_f32 v92, v92, v61, v93
	v_mov_b32_e32 v93, v92
	s_nop 1
	v_permlane32_swap_b32_e32 v92, v93
	v_max_f32_e32 v93, v93, v93
	v_max_f32_e32 v92, v92, v92
	v_max_f32_e32 v92, v92, v93
	v_cmp_lt_f32_e32 vcc, s27, v92
	s_cmp_lg_u64 vcc, 0
	v_add_f32_e32 v186, v201, v108
	s_cselect_b64 s[0:1], -1, 0
	s_cbranch_vccnz .LBB0_1293

.LBB0_1177:
	v_max_f32_e32 v60, v97, v97
	v_max_f32_e32 v61, v96, v96
	v_max_f32_e32 v60, v61, v60
	v_max3_f32 v61, v98, v99, v81
	v_max3_f32 v60, v60, v80, v82
	v_max3_f32 v60, v60, v83, v100
	v_max3_f32 v61, v61, v102, v103
	v_max3_f32 v60, v60, v101, v84
	v_max3_f32 v61, v61, v86, v87
	v_max3_f32 v60, v60, v85, v104
	v_max3_f32 v61, v61, v106, v107
	v_max3_f32 v60, v60, v105, v88
	v_max3_f32 v61, v61, v90, v91
	v_max3_f32 v60, v60, v89, v108
	v_max3_f32 v61, v61, v110, v111
	v_max3_f32 v60, v60, v109, v92
	v_max3_f32 v61, v61, v94, v95
	v_max3_f32 v60, v60, v93, v61
	v_mov_b32_e32 v61, v60
	s_nop 1
	v_permlane32_swap_b32_e32 v60, v61
	v_max_f32_e32 v61, v61, v61
	v_max_f32_e32 v60, v60, v60
	v_max_f32_e32 v60, v60, v61
	v_cmp_lt_f32_e32 vcc, s27, v60
	s_cmp_lg_u64 vcc, 0
	v_cmp_gt_u32_e64 s[8:9], 32, v189
	v_add_f32_e32 v186, v186, v76
	s_cselect_b64 s[0:1], -1, 0
	s_cbranch_vccnz .LBB0_1296

.LBB0_1182:
	v_max_f32_e32 v92, v65, v65
	v_max_f32_e32 v93, v64, v64
	v_max_f32_e32 v92, v93, v92
	v_max3_f32 v93, v66, v67, v49
	v_max3_f32 v92, v92, v48, v50
	v_max3_f32 v92, v92, v51, v68
	v_max3_f32 v93, v93, v70, v71
	v_max3_f32 v92, v92, v69, v52
	v_max3_f32 v93, v93, v54, v55
	v_max3_f32 v92, v92, v53, v72
	v_max3_f32 v93, v93, v74, v75
	v_max3_f32 v92, v92, v73, v56
	v_max3_f32 v93, v93, v58, v59
	v_max3_f32 v92, v92, v57, v76
	v_max3_f32 v93, v93, v78, v79
	v_max3_f32 v92, v92, v77, v60
	v_max3_f32 v93, v93, v62, v63
	v_max3_f32 v92, v92, v61, v93
	v_mov_b32_e32 v93, v92
	s_nop 1
	v_permlane32_swap_b32_e32 v92, v93
	v_max_f32_e32 v93, v93, v93
	v_max_f32_e32 v92, v92, v92
	v_max_f32_e32 v92, v92, v93
	v_cmp_lt_f32_e32 vcc, s27, v92
	s_cmp_lg_u64 vcc, 0
	v_add_f32_e32 v186, v186, v108
	s_cselect_b64 s[0:1], -1, 0
	s_cbranch_vccnz .LBB0_1299

.LBB0_1187:
	v_add_f32_e32 v112, v186, v48
	v_max_f32_e32 v48, v81, v81
	v_max_f32_e32 v49, v80, v80
	v_max_f32_e32 v48, v49, v48
	s_nop 0
	v_max3_f32 v49, v82, v83, v1
	v_max3_f32 v48, v48, v0, v2
	v_max3_f32 v48, v48, v3, v84
	v_max3_f32 v49, v49, v86, v87
	v_max3_f32 v48, v48, v85, v4
	v_max3_f32 v49, v49, v6, v7
	v_max3_f32 v48, v48, v5, v88
	v_max3_f32 v49, v49, v90, v91
	v_max3_f32 v48, v48, v89, v8
	v_max3_f32 v49, v49, v10, v11
	v_max3_f32 v48, v48, v9, v92
	v_max3_f32 v49, v49, v94, v95
	v_max3_f32 v48, v48, v93, v12
	v_max3_f32 v49, v49, v14, v15
	v_max3_f32 v48, v48, v13, v49
	v_mov_b32_e32 v49, v48
	s_nop 1
	v_permlane32_swap_b32_e32 v48, v49
	v_max_f32_e32 v49, v49, v49
	v_max_f32_e32 v48, v48, v48
	v_max_f32_e32 v48, v48, v49
	v_cmp_lt_f32_e32 vcc, s27, v48
	s_cmp_lg_u64 vcc, 0
	s_cselect_b64 s[0:1], -1, 0
	s_cbranch_vccnz .LBB0_1287

; #define WAIT_BAR(N) asm volatile("s_waitcnt vmcnt(" #N ") lgkmcnt(0)\n\ts_barrier":::"memory")
;     ...
;   const bf16*ksrc=Kh+(long)lane*DM+wid*8;
;   const bf16*vsrc=Vh+(long)(16*(wid&3)+(lane>>2))*DM+(wid>>2)*32+(lane&3)*8;
;   const unsigned kdst=lds0+LDS_K+wid*1024, vdst=lds0+LDS_V+wid*1024;
;     ...
;   const int vb0=(int)(lds0+LDS_V)+((lane>>4)&1)*32+(lane&3)*8+(4*hi+((lane&15)>>2))*64;
;   const char*Kbase=shm+LDS_K; bf16x8 kf[8];
;   const lds_cptr shm3=(lds_cptr)shm; const lds_cptr kp0=shm3+LDS_K+hi*1024+r32*16; const lds_cptr vp0=shm3+LDS_V+((lane>>4)&1)*32+(lane&3)*8+(4*hi+((lane&15)>>2))*64;
;   const int NT=(q0+QB)/KVBLK-t0;
;   bf16x8 qr[4]; unsigned long long sel=0ull;
;   const bf16*Qrow=Qw+(long)r32*DM;
;   if(MODE==3){ const int p_=wid*QBLK+r32; const long trow_=list?(long)list[p_<len?p_:len-1]:(long)(q0+p_); Qrow=Q+trow_*DM; }
;   if(MODE==1){
;     #pragma unroll
;     for(int d0=0;d0<4;++d0)qr[d0]=*reinterpret_cast<const bf16x8*>(&Qrow[d0*16+hi*8]);
;     float*km=(float*)(shm+86016);
;     #pragma unroll
;     for(int i=0;i<8;++i){const int e=tid+512*i; km[e]=(ksum[e]+ksum[e+4*64*64])*(1.0f/256.0f);}
;     asm volatile("s_waitcnt vmcnt(0) lgkmcnt(0)\n\ts_barrier":::"memory");
;     float qf[32];
;     #pragma unroll
;     for(int d0=0;d0<4;++d0)
;       #pragma unroll
;       for(int j=0;j<8;++j)qf[d0*8+j]=__uint_as_float(((unsigned)(unsigned short)qr[d0][j])<<16);
;     float t1=-INFINITY,t2=-INFINITY,t3=-INFINITY; int i1=-1,i2=-1,i3=-1;
;     for(int b=0;b<qb;++b){
;       const float*kr=km+b*64+hi*8; float g=0.f;
;       #pragma unroll
;       for(int d0=0;d0<4;++d0)
;         #pragma unroll
;         for(int j=0;j<8;++j)g+=qf[d0*8+j]*kr[d0*16+j];
;       g+=__shfl_xor(g,32);
;       if(g>t3){ if(g>t2){ t3=t2;i3=i2; if(g>t1){t2=t1;i2=i1;t1=g;i1=b;} else {t2=g;i2=b;} } else {t3=g;i3=b;} }
;     }
;     if(i1>=0)sel|=1ull<<i1; if(i2>=0)sel|=1ull<<i2; if(i3>=0)sel|=1ull<<i3;
;   }
;   DMA_K(0,0);DMA_V(0,0);DMA_K(1,SLOTB);
;   if(MODE!=1){
;     #pragma unroll
;     for(int d0=0;d0<4;++d0)qr[d0]=*reinterpret_cast<const bf16x8*>(&Qrow[d0*16+hi*8]);
;   }
;   float mhat=0.f,l_reg=0.f;f32x16 o[2];o[0]=f32x16{};o[1]=f32x16{};f32x16 negm=f32x16{};asm volatile("":"+v"(negm));
;   const int qrel=wid*QBLK+r32;
;     ...
;   bool resc=false;
;     ...
;   f32x16 pA0,pA1,pB0,pB1;
;   int sl_prev=0,sl_cur=0,sl_next=SLOTB;
;     ...
;   DMA_K(2,2*SLOTB);
;   WAIT_BAR(3);
.LBB0_1204:
	s_andn2_b64 vcc, exec, s[0:1]
	s_cbranch_vccnz .LBB0_1075
	s_ashr_i32 s0, s69, 31
	s_lshr_b32 s0, s0, 28
	s_add_i32 s1, s69, s0
	s_ashr_i32 s12, s1, 4
	s_and_b32 s1, s1, -16
	s_sub_i32 s4, s69, s1
	s_and_b32 s32, s32, 5
	s_lshl_b32 s0, s4, 8
	s_or_b32 s32, s32, s0
	s_lshl_b32 s0, s12, 16
	s_or_b32 s32, s32, s0
	s_mov_b32 s82, 0x41000000
	s_bitcmp1_b32 s32, 0
	s_cselect_b32 s82, 0x7f800000, s82
	v_mov_b32_e32 v223, 0
	s_ashr_i32 s30, s4, 2
	s_lshl_b32 s2, s30, 7
	s_ashr_i32 s3, s2, 31
	s_sub_i32 s0, 63, s12
	s_lshl_b64 s[20:21], s[2:3], 1
	s_add_u32 s1, s60, s20
	s_addc_u32 s2, s61, s21
	s_bfe_u32 s31, s4, 0x10001
	s_lshl_b32 s3, s31, 7
	s_add_u32 s1, s1, s3
	s_addc_u32 s2, s2, 0
	s_add_u32 s5, s62, s20
	s_addc_u32 s8, s63, s21
	s_add_u32 s10, s5, s3
	s_addc_u32 s11, s8, 0
	s_add_u32 s3, s64, s20
	s_addc_u32 s8, s65, s21
	s_lshl_b32 s5, s4, 6
	s_and_b32 s9, s5, 64
	s_lshl_b32 s34, s9, 1
	v_mov_b32_e32 v84, v230
	s_add_u32 s22, s3, s34
	s_addc_u32 s23, s8, 0
	v_readfirstlane_b32 s3, v84
	s_ashr_i32 s28, s3, 6
	s_lshl_b32 s8, s0, 8
	s_lshl_b32 s9, s28, 5
	v_and_b32_e32 v200, 63, v84
	s_add_i32 s29, s9, s8
	s_mul_i32 s24, s29, 0x1600
	v_mul_u32_u24_e32 v0, 0xb00, v200
	s_mul_hi_i32 s13, s29, 0x1600
	s_add_u32 s24, s1, s24
	v_lshlrev_b32_e32 v112, 1, v0
	s_addc_u32 s25, s2, s13
	v_lshl_add_u64 v[0:1], s[10:11], 0, v[112:113]
	s_lshl_b32 s10, s28, 3
	s_ashr_i32 s11, s10, 31
	v_lshl_add_u64 v[80:81], s[10:11], 1, v[0:1]
	s_lshl_b32 s1, s28, 4
	v_bfe_u32 v0, v84, 2, 4
	v_and_or_b32 v0, s1, 48, v0
	v_mul_u32_u24_e32 v0, 0xb00, v0
	v_lshlrev_b32_e32 v182, 1, v0
	v_mov_b32_e32 v183, v113
	s_ashr_i32 s1, s3, 3
	v_lshl_add_u64 v[0:1], s[22:23], 0, v[182:183]
	s_and_b32 s22, s1, 0xffffffe0
	s_ashr_i32 s23, s22, 31
	v_lshlrev_b32_e32 v201, 3, v84
	s_lshl_b32 s2, s28, 10
	v_and_b32_e32 v204, 24, v201
	s_cmp_lg_u32 0, -1
	v_and_b32_e32 v202, 31, v84
	v_lshl_add_u64 v[0:1], s[22:23], 1, v[0:1]
	v_lshlrev_b32_e32 v2, 1, v204
	v_mov_b32_e32 v3, v113
	s_cselect_b32 s1, 0, 0
	v_bfe_u32 v203, v84, 5, 1
	v_lshl_add_u64 v[82:83], v[0:1], 0, v[2:3]
	s_add_i32 s69, s2, s1
	v_mul_u32_u24_e32 v0, 0x1600, v202
	v_mov_b32_e32 v1, v113
	s_mov_b32 s1, m0
	s_mov_b32 m0, s69
	s_nop 0
	global_load_lds_dwordx4 v[80:81], off
	s_mov_b32 m0, s1
	s_add_i32 s70, s69, 0x6000
	v_lshl_add_u64 v[0:1], s[24:25], 0, v[0:1]
	s_mov_b32 s1, m0
	s_mov_b32 m0, s70
	s_nop 0
	global_load_lds_dwordx4 v[82:83], off
	s_mov_b32 m0, s1
	v_lshlrev_b32_e32 v190, 4, v203
	v_mov_b32_e32 v191, v113
	v_lshl_add_u64 v[2:3], v[80:81], 0, s[78:79]
	s_add_i32 s1, s69, 0x2000
	s_mov_b32 s13, m0
	s_mov_b32 m0, s1
	s_nop 0
	global_load_lds_dwordx4 v[2:3], off
	s_mov_b32 m0, s13
	v_lshl_add_u64 v[14:15], v[0:1], 0, v[190:191]
	flat_load_dwordx4 v[134:137], v[14:15]
	flat_load_dwordx4 v[122:125], v[14:15] offset:32
	flat_load_dwordx4 v[118:121], v[14:15] offset:64
	flat_load_dwordx4 v[114:117], v[14:15] offset:96
	v_mov_b32_e32 v0, v113
	v_mov_b32_e32 v1, v113
	v_mov_b32_e32 v2, v113
	v_mov_b32_e32 v3, v113
	v_mov_b32_e32 v4, v113
	v_mov_b32_e32 v5, v113
	v_mov_b32_e32 v6, v113
	v_mov_b32_e32 v7, v113
	v_mov_b32_e32 v8, v113
	v_mov_b32_e32 v9, v113
	v_mov_b32_e32 v10, v113
	v_mov_b32_e32 v11, v113
	v_mov_b32_e32 v12, v113
	v_mov_b32_e32 v13, v113
	v_mov_b32_e32 v14, v113
	v_mov_b32_e32 v15, v113
	v_lshlrev_b32_e32 v16, 10, v203
	v_lshlrev_b32_e32 v17, 4, v202
	v_add3_u32 v210, 0, v16, v17
	v_lshl_add_u64 v[16:17], v[80:81], 0, s[94:95]
	s_add_i32 s1, s69, 0x4000
	s_mov_b32 s13, m0
	s_mov_b32 m0, s1
	s_nop 0
	global_load_lds_dwordx4 v[16:17], off
	s_mov_b32 m0, s13
	s_waitcnt vmcnt(3) lgkmcnt(0)
	s_barrier
; __device__ __forceinline__ void cmask(f32x16&p0,f32x16&p1,int jb,int qrel,int hi){
;   const float NEG=NEGV; int kb=64*jb+4*hi;
;   #pragma unroll
;   for(int r=0;r<16;++r){int kv=kb+(r&3)+8*(r>>2); if(kv>qrel)p0[r]=NEG; if(kv+32>qrel)p1[r]=NEG;}
; }
; __device__ __forceinline__ void qkt(f32x16&p0,f32x16&p1,const char*Kslot,const bf16x8*qr,const f32x16&negm,int r32,int hi){
;   const char*kb=Kslot+hi*1024+r32*16;
;   #pragma unroll
;   for(int d0=0;d0<4;++d0){
;     const bf16x8 b0=*reinterpret_cast<const bf16x8*>(kb+d0*2048);
;     const bf16x8 b1=*reinterpret_cast<const bf16x8*>(kb+d0*2048+512);
;     if(d0==0){p0=__builtin_amdgcn_mfma_f32_32x32x16_bf16(b0,qr[0],negm,0,0,0);p1=__builtin_amdgcn_mfma_f32_32x32x16_bf16(b1,qr[0],negm,0,0,0);}
;     else{p0=__builtin_amdgcn_mfma_f32_32x32x16_bf16(b0,qr[d0],p0,0,0,0);p1=__builtin_amdgcn_mfma_f32_32x32x16_bf16(b1,qr[d0],p1,0,0,0);}}
; }
	ds_read_b128 v[32:35], v210
	s_cmp_lg_u32 s0, 0
	s_cselect_b64 s[0:1], -1, 0
	v_lshlrev_b32_e32 v205, 2, v203
	v_or_b32_e32 v208, s9, v202
	s_and_b64 vcc, exec, s[0:1]
	s_waitcnt vmcnt(0) lgkmcnt(0)
	v_mfma_f32_32x32x16_bf16 v[16:31], v[32:35], v[134:137], v[0:15]
	ds_read_b128 v[32:35], v210 offset:512
	s_waitcnt lgkmcnt(0)
	v_mfma_f32_32x32x16_bf16 v[0:15], v[32:35], v[134:137], v[0:15]
	ds_read_b128 v[32:35], v210 offset:2048
	s_waitcnt lgkmcnt(0)
	v_mfma_f32_32x32x16_bf16 v[16:31], v[32:35], v[122:125], v[16:31]
	ds_read_b128 v[32:35], v210 offset:2560
	s_waitcnt lgkmcnt(0)
	v_mfma_f32_32x32x16_bf16 v[0:15], v[32:35], v[122:125], v[0:15]
	ds_read_b128 v[32:35], v210 offset:4096
	s_waitcnt lgkmcnt(0)
	v_mfma_f32_32x32x16_bf16 v[16:31], v[32:35], v[118:121], v[16:31]
	ds_read_b128 v[32:35], v210 offset:4608
	s_waitcnt lgkmcnt(0)
	v_mfma_f32_32x32x16_bf16 v[0:15], v[32:35], v[118:121], v[0:15]
	ds_read_b128 v[32:35], v210 offset:6144
	s_waitcnt lgkmcnt(0)
	v_mfma_f32_32x32x16_bf16 v[16:31], v[32:35], v[114:117], v[16:31]
	ds_read_b128 v[32:35], v210 offset:6656
	s_waitcnt lgkmcnt(0)
	v_mfma_f32_32x32x16_bf16 v[0:15], v[32:35], v[114:117], v[0:15]
	s_nop 15
	s_nop 7
	s_cbranch_vccnz .LBB0_1207
	v_or_b32_e32 v32, 32, v205
	v_cmp_le_i32_e32 vcc, v32, v208
	v_or_b32_e32 v32, 33, v205
	s_nop 7
	v_cndmask_b32_e32 v0, v240, v0, vcc
	v_cmp_lt_i32_e32 vcc, v205, v208
	s_nop 1
	v_cndmask_b32_e32 v17, v240, v17, vcc
	v_cmp_le_i32_e32 vcc, v205, v208
	s_nop 1
	v_cndmask_b32_e32 v16, v240, v16, vcc
	v_cmp_le_i32_e32 vcc, v32, v208
	v_or_b32_e32 v32, 2, v205
	s_nop 0
	v_cndmask_b32_e32 v1, v240, v1, vcc
	v_cmp_le_i32_e32 vcc, v32, v208
	v_or_b32_e32 v32, 34, v205
	s_nop 0
	v_cndmask_b32_e32 v18, v240, v18, vcc
	v_cmp_le_i32_e32 vcc, v32, v208
	v_or_b32_e32 v32, 3, v205
	s_nop 0
	v_cndmask_b32_e32 v2, v240, v2, vcc
	v_cmp_le_i32_e32 vcc, v32, v208
	v_or_b32_e32 v32, 35, v205
	s_nop 0
	v_cndmask_b32_e32 v19, v240, v19, vcc
	v_cmp_le_i32_e32 vcc, v32, v208
	v_or_b32_e32 v32, 8, v205
	s_nop 0
	v_cndmask_b32_e32 v3, v240, v3, vcc
	v_cmp_le_i32_e32 vcc, v32, v208
	v_or_b32_e32 v32, 40, v205
	s_nop 0
	v_cndmask_b32_e32 v20, v240, v20, vcc
	v_cmp_le_i32_e32 vcc, v32, v208
	v_or_b32_e32 v32, 9, v205
	s_nop 0
	v_cndmask_b32_e32 v4, v240, v4, vcc
	v_cmp_le_i32_e32 vcc, v32, v208
	v_or_b32_e32 v32, 41, v205
	s_nop 0
	v_cndmask_b32_e32 v21, v240, v21, vcc
	v_cmp_le_i32_e32 vcc, v32, v208
	v_or_b32_e32 v32, 10, v205
	s_nop 0
	v_cndmask_b32_e32 v5, v240, v5, vcc
	v_cmp_le_i32_e32 vcc, v32, v208
	v_or_b32_e32 v32, 42, v205
	s_nop 0
	v_cndmask_b32_e32 v22, v240, v22, vcc
	v_cmp_le_i32_e32 vcc, v32, v208
	v_or_b32_e32 v32, 11, v205
	s_nop 0
	v_cndmask_b32_e32 v6, v240, v6, vcc
	v_cmp_le_i32_e32 vcc, v32, v208
	v_or_b32_e32 v32, 43, v205
	s_nop 0
	v_cndmask_b32_e32 v23, v240, v23, vcc
	v_cmp_le_i32_e32 vcc, v32, v208
	v_or_b32_e32 v32, 16, v205
	s_nop 0
	v_cndmask_b32_e32 v7, v240, v7, vcc
	v_cmp_le_i32_e32 vcc, v32, v208
	v_or_b32_e32 v32, 48, v205
	s_nop 0
	v_cndmask_b32_e32 v24, v240, v24, vcc
	v_cmp_le_i32_e32 vcc, v32, v208
	v_or_b32_e32 v32, 17, v205
	s_nop 0
	v_cndmask_b32_e32 v8, v240, v8, vcc
	v_cmp_le_i32_e32 vcc, v32, v208
	v_or_b32_e32 v32, 49, v205
	s_nop 0
	v_cndmask_b32_e32 v25, v240, v25, vcc
	v_cmp_le_i32_e32 vcc, v32, v208
	v_or_b32_e32 v32, 18, v205
	s_nop 0
	v_cndmask_b32_e32 v9, v240, v9, vcc
	v_cmp_le_i32_e32 vcc, v32, v208
	v_or_b32_e32 v32, 50, v205
	s_nop 0
	v_cndmask_b32_e32 v26, v240, v26, vcc
	v_cmp_le_i32_e32 vcc, v32, v208
	v_or_b32_e32 v32, 19, v205
	s_nop 0
	v_cndmask_b32_e32 v10, v240, v10, vcc
	v_cmp_le_i32_e32 vcc, v32, v208
	v_or_b32_e32 v32, 51, v205
	s_nop 0
	v_cndmask_b32_e32 v27, v240, v27, vcc
	v_cmp_le_i32_e32 vcc, v32, v208
	v_or_b32_e32 v32, 24, v205
	s_nop 0
	v_cndmask_b32_e32 v11, v240, v11, vcc
	v_cmp_le_i32_e32 vcc, v32, v208
	v_or_b32_e32 v32, 56, v205
	s_nop 0
	v_cndmask_b32_e32 v28, v240, v28, vcc
	v_cmp_le_i32_e32 vcc, v32, v208
	v_or_b32_e32 v32, 25, v205
	s_nop 0
	v_cndmask_b32_e32 v12, v240, v12, vcc
	v_cmp_le_i32_e32 vcc, v32, v208
	v_or_b32_e32 v32, 57, v205
	s_nop 0
	v_cndmask_b32_e32 v29, v240, v29, vcc
	v_cmp_le_i32_e32 vcc, v32, v208
	v_or_b32_e32 v32, 26, v205
	s_nop 0
	v_cndmask_b32_e32 v13, v240, v13, vcc
	v_cmp_le_i32_e32 vcc, v32, v208
	v_or_b32_e32 v32, 58, v205
	s_nop 0
	v_cndmask_b32_e32 v30, v240, v30, vcc
	v_cmp_le_i32_e32 vcc, v32, v208
	v_or_b32_e32 v32, 27, v205
	s_nop 0
	v_cndmask_b32_e32 v14, v240, v14, vcc
	v_cmp_le_i32_e32 vcc, v32, v208
	v_or_b32_e32 v32, 59, v205
	s_nop 0
	v_cndmask_b32_e32 v31, v240, v31, vcc
	v_cmp_le_i32_e32 vcc, v32, v208
	s_nop 1
	v_cndmask_b32_e32 v15, v240, v15, vcc
